# norm loop waits only for its loads (counted vmcnt, rstd store excluded); rwkv fix tile no longer waits for the previous tile's stores before loading
# baseline (speedup 1.0000x reference)
; __device__ __forceinline__ float bf2f(bf16_t v) { return __uint_as_float(((unsigned)v) << 16); }
; __device__ __forceinline__ bf16_t f2bf(float f) { return (bf16_t)(pack2(f, 0.f) & 0xffffu); }
; __device__ __forceinline__ int launder(int x) { asm volatile("" : "+v"(x)); return x; }
; #define MFMA(a, b, c) __builtin_amdgcn_mfma_f32_16x16x32_bf16(a, b, c, 0, 0, 0)
; __device__ __forceinline__ void rwkv_fix_tile(const Params& p, int tile) {
;   const int mb = tile % (NSEG1 / 64), dbh = tile / (NSEG1 / 64), h = dbh & 3, b = (dbh >> 2) & 3, d = dbh >> 4;
;   const int tid = launder(threadIdx.x), lane = tid & 63, w = tid >> 6, fr = lane & 15, fq = lane >> 4;
;   const size_t rowbase = (size_t)b * TPB;
;   const int s0 = mb * 64 + 16 * w;
;   const bf16_t* gp = p.GID + ((size_t)(d * 4 + b) * NSEG1 + s0 + fr) * 256 + h * 64 + fq * 8;
;   const bf16x8 a0 = *(const bf16x8*)gp, a1 = *(const bf16x8*)(gp + 32);
; #pragma unroll
;   for (int nt = 0; nt < 4; ++nt) {
;     const float* sp = p.SMID + ((size_t)(dbh * 64 + nt * 16 + fr)) * 64 + fq * 8;
;     const float4 f0 = *(const float4*)sp, f1 = *(const float4*)(sp + 4), f2 = *(const float4*)(sp + 32), f3 = *(const float4*)(sp + 36);
;     union { unsigned u[4]; bf16x8 v; } b0, b1;
;     b0.u[0] = pack2(f0.x, f0.y); b0.u[1] = pack2(f0.z, f0.w); b0.u[2] = pack2(f1.x, f1.y); b0.u[3] = pack2(f1.z, f1.w);
;     b1.u[0] = pack2(f2.x, f2.y); b1.u[1] = pack2(f2.z, f2.w); b1.u[2] = pack2(f3.x, f3.y); b1.u[3] = pack2(f3.z, f3.w);
;     f32x4 acc = (f32x4){0.f, 0.f, 0.f, 0.f};
;     acc = MFMA(a0, b0.v, acc);
;     acc = MFMA(a1, b1.v, acc);
; #pragma unroll
;     for (int j = 0; j < 4; ++j) {
;       const int st = CSPLIT * 32 + s0 + fq * 4 + j;
;       const int pp = (d == 0) ? st : ((st < 256) ? 255 - st : 4607 - st);
;       bf16_t* yp = p.yR + ((size_t)d * TOK + rowbase + pp) * 256 + h * 64 + nt * 16 + fr;
;       *yp = f2bf(bf2f(*yp) + acc[j]);
.LBB0_123:
	s_mul_i32 s28, s46, 0xaaab
	v_mov_b32_e32 v0, v189
	s_lshr_b32 s44, s28, 20
	s_mul_i32 s28, s44, 24
	v_and_b32_e32 v12, 15, v0
	v_bfe_u32 v13, v0, 4, 2
	v_ashrrev_i32_e32 v0, 2, v0
	s_sub_i32 s28, s46, s28
	s_ashr_i32 s45, s44, 4
	v_and_b32_e32 v0, -16, v0
	s_bfe_u32 s42, s44, 0x20002
	v_lshl_add_u32 v8, s28, 6, v0
	s_lshl_b32 s28, s45, 2
	s_or_b32 s28, s28, s42
	v_ashrrev_i32_e32 v9, 31, v8
	s_mul_i32 s47, s42, 0x1100
	v_mad_i64_i32 v[0:1], s[42:43], s28, v202, v[8:9]
	v_or_b32_e32 v0, v0, v12
	v_lshlrev_b64 v[0:1], 9, v[0:1]
	s_lshl_b32 s28, s44, 7
	v_lshl_or_b32 v16, s44, 6, v12
	v_lshl_add_u64 v[0:1], s[10:11], 0, v[0:1]
	s_and_b32 s28, s28, 0x180
	v_lshlrev_b32_e32 v10, 5, v13
	v_mov_b32_e32 v11, v164
	v_ashrrev_i32_e32 v17, 31, v16
	v_lshl_add_u64 v[0:1], v[0:1], 0, s[28:29]
	v_lshlrev_b32_e32 v2, 4, v13
	v_mov_b32_e32 v3, v164
	v_lshl_add_u64 v[18:19], s[12:13], 0, v[10:11]
	v_lshlrev_b64 v[10:11], 8, v[16:17]
	v_lshl_add_u64 v[4:5], v[0:1], 0, v[2:3]
	s_nop 0
	v_lshl_add_u64 v[28:29], v[18:19], 0, v[10:11]
	global_load_dwordx4 v[0:3], v[4:5], off
	s_nop 0
	global_load_dwordx4 v[4:7], v[4:5], off offset:64
	v_lshl_or_b32 v32, v13, 2, v8
	v_lshlrev_b32_e32 v8, 1, v12
	v_lshlrev_b32_e32 v34, 8, v16
	v_lshl_add_u32 v34, v13, 5, v34
	v_add_u32_e32 v35, 0x1000, v34
	v_add_u32_e32 v36, 0x2000, v34
	v_add_u32_e32 v37, 0x3000, v34
	global_load_dwordx4 v[40:43], v34, s[12:13]
	global_load_dwordx4 v[44:47], v34, s[12:13] offset:16
	global_load_dwordx4 v[48:51], v34, s[12:13] offset:128
	global_load_dwordx4 v[52:55], v34, s[12:13] offset:144
	global_load_dwordx4 v[56:59], v35, s[12:13]
	global_load_dwordx4 v[60:63], v35, s[12:13] offset:16
	global_load_dwordx4 v[64:67], v35, s[12:13] offset:128
	global_load_dwordx4 v[68:71], v35, s[12:13] offset:144
	global_load_dwordx4 v[72:75], v36, s[12:13]
	global_load_dwordx4 v[76:79], v36, s[12:13] offset:16
	global_load_dwordx4 v[80:83], v36, s[12:13] offset:128
	global_load_dwordx4 v[84:87], v36, s[12:13] offset:144
	global_load_dwordx4 v[88:91], v37, s[12:13]
	global_load_dwordx4 v[92:95], v37, s[12:13] offset:16
	global_load_dwordx4 v[96:99], v37, s[12:13] offset:128
	global_load_dwordx4 v[100:103], v37, s[12:13] offset:144
	s_cmp_lt_u32 s44, 16
	s_mulk_i32 s45, 0x4400
	s_cselect_b64 vcc, -1, 0
	s_add_u32 s44, s45, s47
	v_add_u32_e32 v33, 0xb00, v32
	v_cmp_lt_i32_e64 s[42:43], s40, v33
	s_nop 1
	v_cndmask_b32_e64 v38, v201, v203, s[42:43]
	s_add_u32 s42, s0, s28
	s_addc_u32 s43, s1, 0
	v_sub_u32_e32 v24, v38, v33
	v_cndmask_b32_e32 v24, v24, v33, vcc
	v_add_u32_e32 v24, s44, v24
	v_lshl_add_u32 v24, v24, 9, v8
	v_add_u32_e32 v39, 1, v33
	v_sub_u32_e32 v25, v38, v39
	v_cndmask_b32_e32 v25, v25, v39, vcc
	v_add_u32_e32 v25, s44, v25
	v_lshl_add_u32 v25, v25, 9, v8
	v_add_u32_e32 v39, 2, v33
	v_sub_u32_e32 v26, v38, v39
	v_cndmask_b32_e32 v26, v26, v39, vcc
	v_add_u32_e32 v26, s44, v26
	v_lshl_add_u32 v26, v26, 9, v8
	v_add_u32_e32 v39, 3, v33
	v_sub_u32_e32 v27, v38, v39
	v_cndmask_b32_e32 v27, v27, v39, vcc
	v_add_u32_e32 v27, s44, v27
	v_lshl_add_u32 v27, v27, 9, v8
	global_load_ushort v104, v24, s[42:43]
	global_load_ushort v105, v25, s[42:43]
	global_load_ushort v106, v26, s[42:43]
	global_load_ushort v107, v27, s[42:43]
	global_load_ushort v108, v24, s[42:43] offset:32
	global_load_ushort v109, v25, s[42:43] offset:32
	global_load_ushort v110, v26, s[42:43] offset:32
	global_load_ushort v111, v27, s[42:43] offset:32
	global_load_ushort v112, v24, s[42:43] offset:64
	global_load_ushort v113, v25, s[42:43] offset:64
	global_load_ushort v114, v26, s[42:43] offset:64
	global_load_ushort v115, v27, s[42:43] offset:64
	global_load_ushort v116, v24, s[42:43] offset:96
	global_load_ushort v117, v25, s[42:43] offset:96
	global_load_ushort v118, v26, s[42:43] offset:96
	global_load_ushort v119, v27, s[42:43] offset:96
	s_waitcnt vmcnt(0)
; __device__ __forceinline__ float bf2f(bf16_t v) { return __uint_as_float(((unsigned)v) << 16); }
; __device__ __forceinline__ bf16_t f2bf(float f) { return (bf16_t)(pack2(f, 0.f) & 0xffffu); }
; #define MFMA(a, b, c) __builtin_amdgcn_mfma_f32_16x16x32_bf16(a, b, c, 0, 0, 0)
; __device__ __forceinline__ void rwkv_fix_tile(const Params& p, int tile) {
;     ...
;     const float4 f0 = *(const float4*)sp, f1 = *(const float4*)(sp + 4), f2 = *(const float4*)(sp + 32), f3 = *(const float4*)(sp + 36);
;     union { unsigned u[4]; bf16x8 v; } b0, b1;
;     b0.u[0] = pack2(f0.x, f0.y); b0.u[1] = pack2(f0.z, f0.w); b0.u[2] = pack2(f1.x, f1.y); b0.u[3] = pack2(f1.z, f1.w);
;     b1.u[0] = pack2(f2.x, f2.y); b1.u[1] = pack2(f2.z, f2.w); b1.u[2] = pack2(f3.x, f3.y); b1.u[3] = pack2(f3.z, f3.w);
;     f32x4 acc = (f32x4){0.f, 0.f, 0.f, 0.f};
;     acc = MFMA(a0, b0.v, acc);
;     acc = MFMA(a1, b1.v, acc);
; #pragma unroll
;     for (int j = 0; j < 4; ++j) {
;       const int st = CSPLIT * 32 + s0 + fq * 4 + j;
;       const int pp = (d == 0) ? st : ((st < 256) ? 255 - st : 4607 - st);
;       bf16_t* yp = p.yR + ((size_t)d * TOK + rowbase + pp) * 256 + h * 64 + nt * 16 + fr;
;       *yp = f2bf(bf2f(*yp) + acc[j]);
;     }
;   }
; }
; __device__ __forceinline__ void phase_rwkvfix(const Params& p) {
;   for (int t = blockIdx.x; t < 32 * (NSEG1 / 64); t += gridDim.x) rwkv_fix_tile(p, t);
	v_cvt_pk_bf16_f32 v40, v40, v41
	v_cvt_pk_bf16_f32 v41, v42, v43
	v_cvt_pk_bf16_f32 v42, v44, v45
	v_cvt_pk_bf16_f32 v43, v46, v47
	v_cvt_pk_bf16_f32 v48, v48, v49
	v_cvt_pk_bf16_f32 v49, v50, v51
	v_cvt_pk_bf16_f32 v50, v52, v53
	v_cvt_pk_bf16_f32 v51, v54, v55
	v_cvt_pk_bf16_f32 v56, v56, v57
	v_cvt_pk_bf16_f32 v57, v58, v59
	v_cvt_pk_bf16_f32 v58, v60, v61
	v_cvt_pk_bf16_f32 v59, v62, v63
	v_cvt_pk_bf16_f32 v64, v64, v65
	v_cvt_pk_bf16_f32 v65, v66, v67
	v_cvt_pk_bf16_f32 v66, v68, v69
	v_cvt_pk_bf16_f32 v67, v70, v71
	v_cvt_pk_bf16_f32 v72, v72, v73
	v_cvt_pk_bf16_f32 v73, v74, v75
	v_cvt_pk_bf16_f32 v74, v76, v77
	v_cvt_pk_bf16_f32 v75, v78, v79
	v_cvt_pk_bf16_f32 v80, v80, v81
	v_cvt_pk_bf16_f32 v81, v82, v83
	v_cvt_pk_bf16_f32 v82, v84, v85
	v_cvt_pk_bf16_f32 v83, v86, v87
	v_cvt_pk_bf16_f32 v88, v88, v89
	v_cvt_pk_bf16_f32 v89, v90, v91
	v_cvt_pk_bf16_f32 v90, v92, v93
	v_cvt_pk_bf16_f32 v91, v94, v95
	v_cvt_pk_bf16_f32 v96, v96, v97
	v_cvt_pk_bf16_f32 v97, v98, v99
	v_cvt_pk_bf16_f32 v98, v100, v101
	v_cvt_pk_bf16_f32 v99, v102, v103
	s_nop 1
	v_mfma_f32_16x16x32_bf16 v[120:123], v[0:3], v[40:43], 0
	v_mfma_f32_16x16x32_bf16 v[124:127], v[0:3], v[56:59], 0
	v_mfma_f32_16x16x32_bf16 v[128:131], v[0:3], v[72:75], 0
	v_mfma_f32_16x16x32_bf16 v[132:135], v[0:3], v[88:91], 0
	v_mfma_f32_16x16x32_bf16 v[120:123], v[4:7], v[48:51], v[120:123]
	v_mfma_f32_16x16x32_bf16 v[124:127], v[4:7], v[64:67], v[124:127]
	v_mfma_f32_16x16x32_bf16 v[128:131], v[4:7], v[80:83], v[128:131]
	v_mfma_f32_16x16x32_bf16 v[132:135], v[4:7], v[96:99], v[132:135]
	v_lshlrev_b32_e32 v104, 16, v104
	v_lshlrev_b32_e32 v105, 16, v105
	v_lshlrev_b32_e32 v106, 16, v106
	v_lshlrev_b32_e32 v107, 16, v107
	v_lshlrev_b32_e32 v108, 16, v108
	v_lshlrev_b32_e32 v109, 16, v109
	v_lshlrev_b32_e32 v110, 16, v110
	v_lshlrev_b32_e32 v111, 16, v111
	v_lshlrev_b32_e32 v112, 16, v112
	v_lshlrev_b32_e32 v113, 16, v113
	v_lshlrev_b32_e32 v114, 16, v114
	v_lshlrev_b32_e32 v115, 16, v115
	v_lshlrev_b32_e32 v116, 16, v116
	v_lshlrev_b32_e32 v117, 16, v117
	v_lshlrev_b32_e32 v118, 16, v118
	v_lshlrev_b32_e32 v119, 16, v119
	s_nop 7
	v_add_f32_e32 v104, v120, v104
	v_add_f32_e32 v105, v121, v105
	v_add_f32_e32 v106, v122, v106
	v_add_f32_e32 v107, v123, v107
	v_add_f32_e32 v108, v124, v108
	v_add_f32_e32 v109, v125, v109
	v_add_f32_e32 v110, v126, v110
	v_add_f32_e32 v111, v127, v111
	v_add_f32_e32 v112, v128, v112
	v_add_f32_e32 v113, v129, v113
	v_add_f32_e32 v114, v130, v114
	v_add_f32_e32 v115, v131, v115
	v_add_f32_e32 v116, v132, v116
	v_add_f32_e32 v117, v133, v117
	v_add_f32_e32 v118, v134, v118
	v_add_f32_e32 v119, v135, v119
	v_cvt_pk_bf16_f32 v104, v104, v104
	v_cvt_pk_bf16_f32 v105, v105, v105
	v_cvt_pk_bf16_f32 v106, v106, v106
	v_cvt_pk_bf16_f32 v107, v107, v107
	v_cvt_pk_bf16_f32 v108, v108, v108
	v_cvt_pk_bf16_f32 v109, v109, v109
	v_cvt_pk_bf16_f32 v110, v110, v110
	v_cvt_pk_bf16_f32 v111, v111, v111
	v_cvt_pk_bf16_f32 v112, v112, v112
	v_cvt_pk_bf16_f32 v113, v113, v113
	v_cvt_pk_bf16_f32 v114, v114, v114
	v_cvt_pk_bf16_f32 v115, v115, v115
	v_cvt_pk_bf16_f32 v116, v116, v116
	v_cvt_pk_bf16_f32 v117, v117, v117
	v_cvt_pk_bf16_f32 v118, v118, v118
	v_cvt_pk_bf16_f32 v119, v119, v119
	global_store_short v24, v104, s[42:43]
	global_store_short v25, v105, s[42:43]
	global_store_short v26, v106, s[42:43]
	global_store_short v27, v107, s[42:43]
	global_store_short v24, v108, s[42:43] offset:32
	global_store_short v25, v109, s[42:43] offset:32
	global_store_short v26, v110, s[42:43] offset:32
	global_store_short v27, v111, s[42:43] offset:32
	global_store_short v24, v112, s[42:43] offset:64
	global_store_short v25, v113, s[42:43] offset:64
	global_store_short v26, v114, s[42:43] offset:64
	global_store_short v27, v115, s[42:43] offset:64
	global_store_short v24, v116, s[42:43] offset:96
	global_store_short v25, v117, s[42:43] offset:96
	global_store_short v26, v118, s[42:43] offset:96
	global_store_short v27, v119, s[42:43] offset:96
	s_load_dword s28, s[2:3], 0x0
	s_waitcnt lgkmcnt(0)
	s_add_i32 s46, s28, s46
	s_cmpk_gt_i32 s46, 0x2ff
	s_cbranch_scc0 .LBB0_123

; __device__ __forceinline__ void phase_norm(const Params& p, int l) {
;     ...
;     float rstd = rsqrtf(ss * (1.f / 1024.f) + 1e-6f);
;     if (lane == 0) p.rstd[r] = rstd;
; #pragma unroll
;     for (int i = 0; i < 4; ++i) {
;       int k = lane * 4 + 256 * i;
;       float4 n4 = *(const float4*)(nw + k), sc = *(const float4*)(md + 1024 + k), sh = *(const float4*)(md + k);
;       float h0 = v[i].x * rstd * n4.x * (1.f + sc.x) + sh.x;
;       float h1 = v[i].y * rstd * n4.y * (1.f + sc.y) + sh.y;
;       float h2 = v[i].z * rstd * n4.z * (1.f + sc.z) + sh.z;
;       float h3 = v[i].w * rstd * n4.w * (1.f + sc.w) + sh.w;
;       uint2 o;
;       o.x = pack2(h0, h1);
;       o.y = pack2(h2, h3);
;       *(uint2*)(p.hbuf + (size_t)r * 1024 + k) = o;
;     }
.LBB0_1312:
	s_or_b64 exec, exec, s[46:47]
	v_readlane_b32 s0, v251, 48
	v_readlane_b32 s2, v251, 50
	v_readlane_b32 s3, v251, 51
	v_readlane_b32 s1, v251, 49
	v_pk_mul_f32 v[12:13], v[12:13], v[32:33] op_sel_hi:[1,0]
	v_pk_mul_f32 v[14:15], v[14:15], v[32:33] op_sel_hi:[1,0]
	v_lshlrev_b64 v[34:35], 11, v[22:23]
	v_lshl_add_u64 v[34:35], v[20:21], 0, v[34:35]
	v_mov_b32_e32 v25, v164
	v_pk_mul_f32 v[8:9], v[8:9], v[32:33] op_sel_hi:[1,0]
	v_pk_mul_f32 v[10:11], v[10:11], v[32:33] op_sel_hi:[1,0]
	v_mov_b32_e32 v27, v164
	v_pk_mul_f32 v[4:5], v[4:5], v[32:33] op_sel_hi:[1,0]
	v_pk_mul_f32 v[6:7], v[6:7], v[32:33] op_sel_hi:[1,0]
	v_mov_b32_e32 v29, v164
	v_pk_mul_f32 v[0:1], v[0:1], v[32:33] op_sel_hi:[1,0]
	v_pk_mul_f32 v[2:3], v[2:3], v[32:33] op_sel_hi:[1,0]
	s_add_i32 s54, s54, s52
	s_cmpk_gt_i32 s54, 0x10ff
	v_add_u32_e32 v22, s53, v22
	v_readlane_b32 s4, v251, 52
	v_readlane_b32 s5, v251, 53
	v_readlane_b32 s6, v251, 54
	v_readlane_b32 s7, v251, 55
	v_readlane_b32 s8, v251, 56
	v_readlane_b32 s9, v251, 57
	v_readlane_b32 s10, v251, 58
	v_readlane_b32 s11, v251, 59
	v_readlane_b32 s12, v251, 60
	v_readlane_b32 s13, v251, 61
	v_readlane_b32 s14, v251, 62
	v_readlane_b32 s15, v251, 63
	s_waitcnt vmcnt(1)
	v_pk_mul_f32 v[12:13], v[12:13], v[92:93]
	v_pk_mul_f32 v[14:15], v[14:15], v[94:95]
	v_pk_add_f32 v[92:93], v[96:97], 1.0 op_sel_hi:[1,0]
	v_pk_add_f32 v[94:95], v[98:99], 1.0 op_sel_hi:[1,0]
	v_pk_fma_f32 v[12:13], v[12:13], v[92:93], v[100:101]
	v_pk_fma_f32 v[14:15], v[14:15], v[94:95], v[102:103]
	v_cvt_pk_bf16_f32 v12, v12, v13
	v_cvt_pk_bf16_f32 v13, v14, v15
	global_store_dwordx2 v[34:35], v[12:13], off
	v_pk_mul_f32 v[8:9], v[8:9], v[56:57]
	v_pk_mul_f32 v[10:11], v[10:11], v[58:59]
	v_pk_add_f32 v[56:57], v[68:69], 1.0 op_sel_hi:[1,0]
	v_pk_add_f32 v[58:59], v[70:71], 1.0 op_sel_hi:[1,0]
	v_pk_fma_f32 v[8:9], v[8:9], v[56:57], v[80:81]
	v_pk_fma_f32 v[10:11], v[10:11], v[58:59], v[82:83]
	v_cvt_pk_bf16_f32 v8, v8, v9
	v_cvt_pk_bf16_f32 v9, v10, v11
	global_store_dwordx2 v[34:35], v[8:9], off offset:512
	v_pk_mul_f32 v[4:5], v[4:5], v[60:61]
	v_pk_mul_f32 v[6:7], v[6:7], v[62:63]
	v_pk_add_f32 v[60:61], v[72:73], 1.0 op_sel_hi:[1,0]
	v_pk_add_f32 v[62:63], v[74:75], 1.0 op_sel_hi:[1,0]
	v_pk_fma_f32 v[4:5], v[4:5], v[60:61], v[84:85]
	v_pk_fma_f32 v[6:7], v[6:7], v[62:63], v[86:87]
	v_cvt_pk_bf16_f32 v4, v4, v5
	v_cvt_pk_bf16_f32 v5, v6, v7
	global_store_dwordx2 v[34:35], v[4:5], off offset:1024
	v_pk_mul_f32 v[0:1], v[0:1], v[64:65]
	v_pk_mul_f32 v[2:3], v[2:3], v[66:67]
	v_pk_add_f32 v[64:65], v[76:77], 1.0 op_sel_hi:[1,0]
	v_pk_add_f32 v[66:67], v[78:79], 1.0 op_sel_hi:[1,0]
	v_pk_fma_f32 v[0:1], v[0:1], v[64:65], v[88:89]
	v_pk_fma_f32 v[2:3], v[2:3], v[66:67], v[90:91]
	v_cvt_pk_bf16_f32 v0, v0, v1
	v_cvt_pk_bf16_f32 v1, v2, v3
	global_store_dwordx2 v[34:35], v[0:1], off offset:1536
	s_cbranch_scc1 .LBB0_1327
